# attention back to single f32 ops (no packed VOP3P beside MFMAs), scalar O rescale; select passes unpacked
# speedup vs baseline: 1.0217x; 1.0050x over previous
.Lat_full_0:
	v_cmp_neq_f32_e32 vcc, 1.0, v232
	s_cbranch_vccz .Lat_nors_f0
	v_mul_f32_e32 v0, v232, v0
	v_mul_f32_e32 v1, v232, v1
	v_mul_f32_e32 v2, v232, v2
	v_mul_f32_e32 v3, v232, v3
	v_mul_f32_e32 v4, v232, v4
	v_mul_f32_e32 v5, v232, v5
	v_mul_f32_e32 v6, v232, v6
	v_mul_f32_e32 v7, v232, v7
	v_mul_f32_e32 v8, v232, v8
	v_mul_f32_e32 v9, v232, v9
	v_mul_f32_e32 v10, v232, v10
	v_mul_f32_e32 v11, v232, v11
	v_mul_f32_e32 v12, v232, v12
	v_mul_f32_e32 v13, v232, v13
	v_mul_f32_e32 v14, v232, v14
	v_mul_f32_e32 v15, v232, v15
	v_mul_f32_e32 v16, v232, v16
	v_mul_f32_e32 v17, v232, v17
	v_mul_f32_e32 v18, v232, v18
	v_mul_f32_e32 v19, v232, v19
	v_mul_f32_e32 v20, v232, v20
	v_mul_f32_e32 v21, v232, v21
	v_mul_f32_e32 v22, v232, v22
	v_mul_f32_e32 v23, v232, v23
	v_mul_f32_e32 v24, v232, v24
	v_mul_f32_e32 v25, v232, v25
	v_mul_f32_e32 v26, v232, v26
	v_mul_f32_e32 v27, v232, v27
	v_mul_f32_e32 v28, v232, v28
	v_mul_f32_e32 v29, v232, v29
	v_mul_f32_e32 v30, v232, v30
	v_mul_f32_e32 v31, v232, v31

.Lat_last_0:
	ds_read_b64_tr_b16 v[154:155], v227 offset:0
	ds_read_b64_tr_b16 v[156:157], v227 offset:1024
	ds_read_b64_tr_b16 v[158:159], v228 offset:0
	ds_read_b64_tr_b16 v[160:161], v228 offset:1024
	ds_read_b64_tr_b16 v[162:163], v227 offset:2048
	ds_read_b64_tr_b16 v[164:165], v227 offset:3072
	ds_read_b64_tr_b16 v[166:167], v228 offset:2048
	v_cmp_neq_f32_e32 vcc, 1.0, v232
	s_cbranch_vccz .Lat_nors_l0
	v_mul_f32_e32 v0, v232, v0
	v_mul_f32_e32 v1, v232, v1
	v_mul_f32_e32 v2, v232, v2
	v_mul_f32_e32 v3, v232, v3
	v_mul_f32_e32 v4, v232, v4
	v_mul_f32_e32 v5, v232, v5
	v_mul_f32_e32 v6, v232, v6
	v_mul_f32_e32 v7, v232, v7
	v_mul_f32_e32 v8, v232, v8
	v_mul_f32_e32 v9, v232, v9
	v_mul_f32_e32 v10, v232, v10
	v_mul_f32_e32 v11, v232, v11
	v_mul_f32_e32 v12, v232, v12
	v_mul_f32_e32 v13, v232, v13
	v_mul_f32_e32 v14, v232, v14
	v_mul_f32_e32 v15, v232, v15
	v_mul_f32_e32 v16, v232, v16
	v_mul_f32_e32 v17, v232, v17
	v_mul_f32_e32 v18, v232, v18
	v_mul_f32_e32 v19, v232, v19
	v_mul_f32_e32 v20, v232, v20
	v_mul_f32_e32 v21, v232, v21
	v_mul_f32_e32 v22, v232, v22
	v_mul_f32_e32 v23, v232, v23
	v_mul_f32_e32 v24, v232, v24
	v_mul_f32_e32 v25, v232, v25
	v_mul_f32_e32 v26, v232, v26
	v_mul_f32_e32 v27, v232, v27
	v_mul_f32_e32 v28, v232, v28
	v_mul_f32_e32 v29, v232, v29
	v_mul_f32_e32 v30, v232, v30
	v_mul_f32_e32 v31, v232, v31

.Lat_last_1:
	ds_read_b64_tr_b16 v[154:155], v227 offset:8192
	ds_read_b64_tr_b16 v[156:157], v227 offset:9216
	ds_read_b64_tr_b16 v[158:159], v228 offset:8192
	ds_read_b64_tr_b16 v[160:161], v228 offset:9216
	ds_read_b64_tr_b16 v[162:163], v227 offset:10240
	ds_read_b64_tr_b16 v[164:165], v227 offset:11264
	ds_read_b64_tr_b16 v[166:167], v228 offset:10240
	v_cmp_neq_f32_e32 vcc, 1.0, v232
	s_cbranch_vccz .Lat_nors_l1
	v_mul_f32_e32 v0, v232, v0
	v_mul_f32_e32 v1, v232, v1
	v_mul_f32_e32 v2, v232, v2
	v_mul_f32_e32 v3, v232, v3
	v_mul_f32_e32 v4, v232, v4
	v_mul_f32_e32 v5, v232, v5
	v_mul_f32_e32 v6, v232, v6
	v_mul_f32_e32 v7, v232, v7
	v_mul_f32_e32 v8, v232, v8
	v_mul_f32_e32 v9, v232, v9
	v_mul_f32_e32 v10, v232, v10
	v_mul_f32_e32 v11, v232, v11
	v_mul_f32_e32 v12, v232, v12
	v_mul_f32_e32 v13, v232, v13
	v_mul_f32_e32 v14, v232, v14
	v_mul_f32_e32 v15, v232, v15
	v_mul_f32_e32 v16, v232, v16
	v_mul_f32_e32 v17, v232, v17
	v_mul_f32_e32 v18, v232, v18
	v_mul_f32_e32 v19, v232, v19
	v_mul_f32_e32 v20, v232, v20
	v_mul_f32_e32 v21, v232, v21
	v_mul_f32_e32 v22, v232, v22
	v_mul_f32_e32 v23, v232, v23
	v_mul_f32_e32 v24, v232, v24
	v_mul_f32_e32 v25, v232, v25
	v_mul_f32_e32 v26, v232, v26
	v_mul_f32_e32 v27, v232, v27
	v_mul_f32_e32 v28, v232, v28
	v_mul_f32_e32 v29, v232, v29
	v_mul_f32_e32 v30, v232, v30
	v_mul_f32_e32 v31, v232, v31

.Lat_last_2:
	ds_read_b64_tr_b16 v[154:155], v227 offset:16384
	ds_read_b64_tr_b16 v[156:157], v227 offset:17408
	ds_read_b64_tr_b16 v[158:159], v228 offset:16384
	ds_read_b64_tr_b16 v[160:161], v228 offset:17408
	ds_read_b64_tr_b16 v[162:163], v227 offset:18432
	ds_read_b64_tr_b16 v[164:165], v227 offset:19456
	ds_read_b64_tr_b16 v[166:167], v228 offset:18432
	v_cmp_neq_f32_e32 vcc, 1.0, v232
	s_cbranch_vccz .Lat_nors_l2
	v_mul_f32_e32 v0, v232, v0
	v_mul_f32_e32 v1, v232, v1
	v_mul_f32_e32 v2, v232, v2
	v_mul_f32_e32 v3, v232, v3
	v_mul_f32_e32 v4, v232, v4
	v_mul_f32_e32 v5, v232, v5
	v_mul_f32_e32 v6, v232, v6
	v_mul_f32_e32 v7, v232, v7
	v_mul_f32_e32 v8, v232, v8
	v_mul_f32_e32 v9, v232, v9
	v_mul_f32_e32 v10, v232, v10
	v_mul_f32_e32 v11, v232, v11
	v_mul_f32_e32 v12, v232, v12
	v_mul_f32_e32 v13, v232, v13
	v_mul_f32_e32 v14, v232, v14
	v_mul_f32_e32 v15, v232, v15
	v_mul_f32_e32 v16, v232, v16
	v_mul_f32_e32 v17, v232, v17
	v_mul_f32_e32 v18, v232, v18
	v_mul_f32_e32 v19, v232, v19
	v_mul_f32_e32 v20, v232, v20
	v_mul_f32_e32 v21, v232, v21
	v_mul_f32_e32 v22, v232, v22
	v_mul_f32_e32 v23, v232, v23
	v_mul_f32_e32 v24, v232, v24
	v_mul_f32_e32 v25, v232, v25
	v_mul_f32_e32 v26, v232, v26
	v_mul_f32_e32 v27, v232, v27
	v_mul_f32_e32 v28, v232, v28
	v_mul_f32_e32 v29, v232, v29
	v_mul_f32_e32 v30, v232, v30
	v_mul_f32_e32 v31, v232, v31

.Lat_last_3:
	ds_read_b64_tr_b16 v[154:155], v227 offset:24576
	ds_read_b64_tr_b16 v[156:157], v227 offset:25600
	ds_read_b64_tr_b16 v[158:159], v228 offset:24576
	ds_read_b64_tr_b16 v[160:161], v228 offset:25600
	ds_read_b64_tr_b16 v[162:163], v227 offset:26624
	ds_read_b64_tr_b16 v[164:165], v227 offset:27648
	ds_read_b64_tr_b16 v[166:167], v228 offset:26624
	v_cmp_neq_f32_e32 vcc, 1.0, v232
	s_cbranch_vccz .Lat_nors_l3
	v_mul_f32_e32 v0, v232, v0
	v_mul_f32_e32 v1, v232, v1
	v_mul_f32_e32 v2, v232, v2
	v_mul_f32_e32 v3, v232, v3
	v_mul_f32_e32 v4, v232, v4
	v_mul_f32_e32 v5, v232, v5
	v_mul_f32_e32 v6, v232, v6
	v_mul_f32_e32 v7, v232, v7
	v_mul_f32_e32 v8, v232, v8
	v_mul_f32_e32 v9, v232, v9
	v_mul_f32_e32 v10, v232, v10
	v_mul_f32_e32 v11, v232, v11
	v_mul_f32_e32 v12, v232, v12
	v_mul_f32_e32 v13, v232, v13
	v_mul_f32_e32 v14, v232, v14
	v_mul_f32_e32 v15, v232, v15
	v_mul_f32_e32 v16, v232, v16
	v_mul_f32_e32 v17, v232, v17
	v_mul_f32_e32 v18, v232, v18
	v_mul_f32_e32 v19, v232, v19
	v_mul_f32_e32 v20, v232, v20
	v_mul_f32_e32 v21, v232, v21
	v_mul_f32_e32 v22, v232, v22
	v_mul_f32_e32 v23, v232, v23
	v_mul_f32_e32 v24, v232, v24
	v_mul_f32_e32 v25, v232, v25
	v_mul_f32_e32 v26, v232, v26
	v_mul_f32_e32 v27, v232, v27
	v_mul_f32_e32 v28, v232, v28
	v_mul_f32_e32 v29, v232, v29
	v_mul_f32_e32 v30, v232, v30
	v_mul_f32_e32 v31, v232, v31
